# barrier: every workgroup polls the monotonic TOP arrival counter (TOP >= (gen+1)*nx) - TOPGEN and XGEN forwarding adds removed
# speedup vs baseline: 1.0036x; 1.0013x over previous
; __device__ __forceinline__ unsigned xb_ld(unsigned* p)              { return __hip_atomic_load(p, __ATOMIC_RELAXED, __HIP_MEMORY_SCOPE_AGENT); }
; __device__ __forceinline__ unsigned xb_add(unsigned* p, unsigned v) { return __hip_atomic_fetch_add(p, v, __ATOMIC_RELAXED, __HIP_MEMORY_SCOPE_AGENT); }
; #define XB_SPIN(cond, bar) do { unsigned _sp = 0; while (cond) { __builtin_amdgcn_s_sleep(1); \
;     if ((++_sp & 255u) == 0u) { if (xb_ld(&(bar)[XB_TMO])) break; if (_sp > XB_SPIN_CAP) { atomicAdd(&(bar)[XB_TMO], 1u); break; } } } } while (0)
; __device__ __forceinline__ void xcd_barrier(const XcdBarrier& b) {
;     ...
;         const unsigned old = xb_add(&bar[XB_XSUB(b.x)], 1u);
;         const unsigned gen = old / nloc;
;         if (old + 1u == (gen + 1u) * nloc) {
;             __builtin_amdgcn_fence(__ATOMIC_RELEASE, "agent");
;             asm volatile("s_waitcnt vmcnt(0)" ::: "memory");
;             const unsigned og = xb_add(&bar[XB_TOP], 1u);
;             const unsigned tg = og / nx;
;             if (og + 1u == (tg + 1u) * nx) xb_add(&bar[XB_TOPGEN], 1u);
;             else XB_SPIN(xb_ld(&bar[XB_TOPGEN]) == tg, bar);
;             __builtin_amdgcn_fence(__ATOMIC_ACQUIRE, "agent");
;             xb_add(&bar[XB_XGEN(b.x)], 1u);
;             asm volatile("s_waitcnt vmcnt(0)" ::: "memory");
;         } else {
;             XB_SPIN(xb_ld(&bar[XB_XGEN(b.x)]) == gen, bar);
.LBB0_72:
	s_or_b64 exec, exec, s[8:9]
	v_cvt_f32_u32_e32 v4, v2
	s_waitcnt vmcnt(0)
	v_readfirstlane_b32 s6, v3
	v_sub_u32_e32 v3, 0, v2
	v_rcp_iflag_f32_e32 v4, v4
	v_add_u32_e32 v5, s6, v1
	v_mul_f32_e32 v4, 0x4f7ffffe, v4
	v_cvt_u32_f32_e32 v4, v4
	v_mul_lo_u32 v1, v3, v4
	v_mul_hi_u32 v1, v4, v1
	v_add_u32_e32 v1, v4, v1
	v_mul_hi_u32 v1, v5, v1
	v_mul_lo_u32 v3, v1, v2
	v_sub_u32_e32 v3, v5, v3
	v_add_u32_e32 v4, 1, v1
	v_cmp_ge_u32_e32 vcc, v3, v2
	s_nop 1
	v_cndmask_b32_e32 v1, v1, v4, vcc
	v_sub_u32_e32 v4, v3, v2
	v_cndmask_b32_e32 v3, v3, v4, vcc
	v_add_u32_e32 v4, 1, v1
	v_cmp_ge_u32_e32 vcc, v3, v2
	v_add_u32_e32 v3, 1, v5
	s_nop 0
	v_cndmask_b32_e32 v1, v1, v4, vcc
	v_mul_lo_u32 v4, v2, v1
	v_add_u32_e32 v2, v4, v2
	v_cmp_ne_u32_e32 vcc, v3, v2
	s_and_saveexec_b64 s[6:7], vcc
	s_xor_b64 s[6:7], exec, s[6:7]
	s_cbranch_execz .LBB0_86
	s_waitcnt lgkmcnt(0)
	v_add_u32_e32 v1, 1, v1
	v_mul_lo_u32 v1, v1, v0
	v_mov_b32_e32 v0, 0x2000
	s_add_u32 s12, s2, 0x81000
	s_addc_u32 s13, s3, 0
	global_load_dword v0, v0, s[12:13] offset:1024 sc1
	s_add_u32 s12, s2, 0x83400
	s_addc_u32 s13, s3, 0
	s_waitcnt vmcnt(0)
	v_cmp_lt_u32_e32 vcc, v0, v1
	s_and_saveexec_b64 s[8:9], vcc
	s_cbranch_execz .LBB0_85
	s_add_u32 s10, s2, 0x80200
	s_addc_u32 s11, s3, 0
	s_mov_b32 s24, 1
	s_mov_b64 s[14:15], 0
	v_mov_b32_e32 v0, 0
	s_branch .LBB0_76

; __device__ __forceinline__ unsigned xb_ld(unsigned* p)              { return __hip_atomic_load(p, __ATOMIC_RELAXED, __HIP_MEMORY_SCOPE_AGENT); }
; #define XB_SPIN(cond, bar) do { unsigned _sp = 0; while (cond) { __builtin_amdgcn_s_sleep(1); \
;     if ((++_sp & 255u) == 0u) { if (xb_ld(&(bar)[XB_TMO])) break; if (_sp > XB_SPIN_CAP) { atomicAdd(&(bar)[XB_TMO], 1u); break; } } } } while (0)
; __device__ __forceinline__ void xcd_barrier(const XcdBarrier& b) {
;     ...
;             XB_SPIN(xb_ld(&bar[XB_XGEN(b.x)]) == gen, bar);
.LBB0_80:
	global_load_dword v2, v0, s[12:13] sc1
	s_add_i32 s24, s24, 1
	s_mov_b64 s[20:21], -1
	s_waitcnt vmcnt(0)
	v_cmp_ge_u32_e32 vcc, v2, v1
	s_orn2_b64 s[18:19], vcc, exec
	s_branch .LBB0_75

; __device__ __forceinline__ unsigned xb_ld(unsigned* p)              { return __hip_atomic_load(p, __ATOMIC_RELAXED, __HIP_MEMORY_SCOPE_AGENT); }
; __device__ __forceinline__ unsigned xb_add(unsigned* p, unsigned v) { return __hip_atomic_fetch_add(p, v, __ATOMIC_RELAXED, __HIP_MEMORY_SCOPE_AGENT); }
; #define XB_SPIN(cond, bar) do { unsigned _sp = 0; while (cond) { __builtin_amdgcn_s_sleep(1); \
;     if ((++_sp & 255u) == 0u) { if (xb_ld(&(bar)[XB_TMO])) break; if (_sp > XB_SPIN_CAP) { atomicAdd(&(bar)[XB_TMO], 1u); break; } } } } while (0)
; __device__ __forceinline__ void xcd_barrier(const XcdBarrier& b) {
;     ...
;         if (old + 1u == (gen + 1u) * nloc) {
;             __builtin_amdgcn_fence(__ATOMIC_RELEASE, "agent");
;             asm volatile("s_waitcnt vmcnt(0)" ::: "memory");
;             const unsigned og = xb_add(&bar[XB_TOP], 1u);
;             const unsigned tg = og / nx;
;             if (og + 1u == (tg + 1u) * nx) xb_add(&bar[XB_TOPGEN], 1u);
;             else XB_SPIN(xb_ld(&bar[XB_TOPGEN]) == tg, bar);
;             __builtin_amdgcn_fence(__ATOMIC_ACQUIRE, "agent");
;             xb_add(&bar[XB_XGEN(b.x)], 1u);
;             asm volatile("s_waitcnt vmcnt(0)" ::: "memory");
.LBB0_89:
	s_or_b64 exec, exec, s[8:9]
	v_cvt_f32_u32_e32 v3, v0
	s_waitcnt vmcnt(0)
	v_readfirstlane_b32 s6, v2
	s_add_u32 s8, s2, 0x83500
	s_addc_u32 s9, s3, 0
	v_rcp_iflag_f32_e32 v3, v3
	v_add_u32_e32 v1, s6, v1
	v_add_u32_e32 v4, 1, v1
	s_mov_b64 s[10:11], 0
	v_mul_f32_e32 v2, 0x4f7ffffe, v3
	v_cvt_u32_f32_e32 v2, v2
	v_sub_u32_e32 v3, 0, v0
	v_mul_lo_u32 v3, v3, v2
	v_mul_hi_u32 v3, v2, v3
	v_add_u32_e32 v2, v2, v3
	v_mul_hi_u32 v2, v1, v2
	v_mul_lo_u32 v3, v2, v0
	v_sub_u32_e32 v1, v1, v3
	v_add_u32_e32 v5, 1, v2
	v_cmp_ge_u32_e32 vcc, v1, v0
	v_sub_u32_e32 v3, v1, v0
	s_nop 0
	v_cndmask_b32_e32 v2, v2, v5, vcc
	v_cndmask_b32_e32 v1, v1, v3, vcc
	v_add_u32_e32 v3, 1, v2
	v_cmp_ge_u32_e32 vcc, v1, v0
	s_nop 1
	v_cndmask_b32_e32 v2, v2, v3, vcc
	v_mul_lo_u32 v1, v0, v2
	v_add_u32_e32 v0, v1, v0
	v_mov_b32_e32 v2, v0
	v_cmp_ne_u32_e32 vcc, v4, v0
	v_mov_b64_e32 v[0:1], s[8:9]
	s_and_saveexec_b64 s[6:7], vcc
	s_cbranch_execz .LBB0_101
	v_mov_b32_e32 v0, 0
	global_load_dword v1, v0, s[8:9] offset:-256 sc1
	s_mov_b64 s[14:15], 0
	s_waitcnt vmcnt(0)
	v_cmp_lt_u32_e32 vcc, v1, v2
	s_and_saveexec_b64 s[12:13], vcc
	s_cbranch_execz .LBB0_100
	s_add_u32 s10, s2, 0x80200
	s_addc_u32 s11, s3, 0
	s_mov_b32 s22, 1
	s_mov_b64 s[2:3], 0
	s_branch .LBB0_93

; __device__ __forceinline__ unsigned xb_ld(unsigned* p)              { return __hip_atomic_load(p, __ATOMIC_RELAXED, __HIP_MEMORY_SCOPE_AGENT); }
; #define XB_SPIN(cond, bar) do { unsigned _sp = 0; while (cond) { __builtin_amdgcn_s_sleep(1); \
;     if ((++_sp & 255u) == 0u) { if (xb_ld(&(bar)[XB_TMO])) break; if (_sp > XB_SPIN_CAP) { atomicAdd(&(bar)[XB_TMO], 1u); break; } } } } while (0)
; __device__ __forceinline__ void xcd_barrier(const XcdBarrier& b) {
;     ...
;             else XB_SPIN(xb_ld(&bar[XB_TOPGEN]) == tg, bar);
.LBB0_97:
	global_load_dword v1, v0, s[8:9] offset:-256 sc1
	s_add_i32 s22, s22, 1
	s_mov_b64 s[16:17], -1
	s_waitcnt vmcnt(0)
	v_cmp_ge_u32_e32 vcc, v1, v2
	s_orn2_b64 s[20:21], vcc, exec
	s_branch .LBB0_92

; __device__ __forceinline__ unsigned xb_add(unsigned* p, unsigned v) { return __hip_atomic_fetch_add(p, v, __ATOMIC_RELAXED, __HIP_MEMORY_SCOPE_AGENT); }
; __device__ __forceinline__ void xcd_barrier(const XcdBarrier& b) {
;     ...
;             __builtin_amdgcn_fence(__ATOMIC_ACQUIRE, "agent");
;             xb_add(&bar[XB_XGEN(b.x)], 1u);
;             asm volatile("s_waitcnt vmcnt(0)" ::: "memory");
.LBB0_103:
	s_or_b64 exec, exec, s[2:3]
	s_mov_b64 s[2:3], exec
	v_mbcnt_lo_u32_b32 v0, s2, 0
	v_mbcnt_hi_u32_b32 v0, s3, v0
	v_cmp_eq_u32_e32 vcc, 0, v0
	s_waitcnt vmcnt(0)
	buffer_inv sc1
	s_and_saveexec_b64 s[6:7], vcc
	s_cbranch_execz .LBB0_105
	s_bcnt1_i32_b64 s2, s[2:3]
	v_mov_b32_e32 v0, 0x2000
	v_mov_b32_e32 v1, s2
.LBB0_105:
	s_or_b64 exec, exec, s[6:7]
	s_waitcnt vmcnt(0)

; __device__ __forceinline__ unsigned xb_ld(unsigned* p)              { return __hip_atomic_load(p, __ATOMIC_RELAXED, __HIP_MEMORY_SCOPE_AGENT); }
; __device__ __forceinline__ unsigned xb_add(unsigned* p, unsigned v) { return __hip_atomic_fetch_add(p, v, __ATOMIC_RELAXED, __HIP_MEMORY_SCOPE_AGENT); }
; #define XB_SPIN(cond, bar) do { unsigned _sp = 0; while (cond) { __builtin_amdgcn_s_sleep(1); \
;     if ((++_sp & 255u) == 0u) { if (xb_ld(&(bar)[XB_TMO])) break; if (_sp > XB_SPIN_CAP) { atomicAdd(&(bar)[XB_TMO], 1u); break; } } } } while (0)
; __device__ __forceinline__ void xcd_barrier(const XcdBarrier& b) {
;     ...
;         const unsigned old = xb_add(&bar[XB_XSUB(b.x)], 1u);
;         const unsigned gen = old / nloc;
;         if (old + 1u == (gen + 1u) * nloc) {
;             __builtin_amdgcn_fence(__ATOMIC_RELEASE, "agent");
;             asm volatile("s_waitcnt vmcnt(0)" ::: "memory");
;             const unsigned og = xb_add(&bar[XB_TOP], 1u);
;             const unsigned tg = og / nx;
;             if (og + 1u == (tg + 1u) * nx) xb_add(&bar[XB_TOPGEN], 1u);
;             else XB_SPIN(xb_ld(&bar[XB_TOPGEN]) == tg, bar);
;             __builtin_amdgcn_fence(__ATOMIC_ACQUIRE, "agent");
;             xb_add(&bar[XB_XGEN(b.x)], 1u);
;             asm volatile("s_waitcnt vmcnt(0)" ::: "memory");
;         } else {
;             XB_SPIN(xb_ld(&bar[XB_XGEN(b.x)]) == gen, bar);
.LBB0_215:
	s_or_b64 exec, exec, s[8:9]
	v_cvt_f32_u32_e32 v4, v2
	s_waitcnt vmcnt(0)
	v_readfirstlane_b32 s6, v3
	v_sub_u32_e32 v3, 0, v2
	v_rcp_iflag_f32_e32 v4, v4
	v_add_u32_e32 v5, s6, v1
	v_mul_f32_e32 v4, 0x4f7ffffe, v4
	v_cvt_u32_f32_e32 v4, v4
	v_mul_lo_u32 v1, v3, v4
	v_mul_hi_u32 v1, v4, v1
	v_add_u32_e32 v1, v4, v1
	v_mul_hi_u32 v1, v5, v1
	v_mul_lo_u32 v3, v1, v2
	v_sub_u32_e32 v3, v5, v3
	v_add_u32_e32 v4, 1, v1
	v_cmp_ge_u32_e32 vcc, v3, v2
	s_nop 1
	v_cndmask_b32_e32 v1, v1, v4, vcc
	v_sub_u32_e32 v4, v3, v2
	v_cndmask_b32_e32 v3, v3, v4, vcc
	v_add_u32_e32 v4, 1, v1
	v_cmp_ge_u32_e32 vcc, v3, v2
	v_add_u32_e32 v3, 1, v5
	s_nop 0
	v_cndmask_b32_e32 v1, v1, v4, vcc
	v_mul_lo_u32 v4, v2, v1
	v_add_u32_e32 v2, v4, v2
	v_cmp_ne_u32_e32 vcc, v3, v2
	s_and_saveexec_b64 s[6:7], vcc
	s_xor_b64 s[6:7], exec, s[6:7]
	s_cbranch_execz .LBB0_229
	s_waitcnt lgkmcnt(0)
	v_add_u32_e32 v1, 1, v1
	v_mul_lo_u32 v1, v1, v0
	s_add_u32 s12, s2, 0x81000
	s_addc_u32 s13, s3, 0
	global_load_dword v0, v237, s[12:13] offset:1024 sc1
	s_add_u32 s12, s2, 0x83400
	s_addc_u32 s13, s3, 0
	s_waitcnt vmcnt(0)
	v_cmp_lt_u32_e32 vcc, v0, v1
	s_and_saveexec_b64 s[8:9], vcc
	s_cbranch_execz .LBB0_228
	s_add_u32 s10, s2, 0x80200
	s_mov_b64 s[26:27], s[24:25]
	s_addc_u32 s11, s3, 0
	s_mov_b32 s24, 1
	s_mov_b64 s[14:15], 0
	s_branch .LBB0_219

; __device__ __forceinline__ unsigned xb_ld(unsigned* p)              { return __hip_atomic_load(p, __ATOMIC_RELAXED, __HIP_MEMORY_SCOPE_AGENT); }
; #define XB_SPIN(cond, bar) do { unsigned _sp = 0; while (cond) { __builtin_amdgcn_s_sleep(1); \
;     if ((++_sp & 255u) == 0u) { if (xb_ld(&(bar)[XB_TMO])) break; if (_sp > XB_SPIN_CAP) { atomicAdd(&(bar)[XB_TMO], 1u); break; } } } } while (0)
; __device__ __forceinline__ void xcd_barrier(const XcdBarrier& b) {
;     ...
;             XB_SPIN(xb_ld(&bar[XB_XGEN(b.x)]) == gen, bar);
.LBB0_223:
	global_load_dword v0, v113, s[12:13] sc1
	s_add_i32 s24, s24, 1
	s_mov_b64 s[20:21], -1
	s_waitcnt vmcnt(0)
	v_cmp_ge_u32_e32 vcc, v0, v1
	s_orn2_b64 s[18:19], vcc, exec
	s_branch .LBB0_218

; __device__ __forceinline__ unsigned xb_ld(unsigned* p)              { return __hip_atomic_load(p, __ATOMIC_RELAXED, __HIP_MEMORY_SCOPE_AGENT); }
; __device__ __forceinline__ unsigned xb_add(unsigned* p, unsigned v) { return __hip_atomic_fetch_add(p, v, __ATOMIC_RELAXED, __HIP_MEMORY_SCOPE_AGENT); }
; #define XB_SPIN(cond, bar) do { unsigned _sp = 0; while (cond) { __builtin_amdgcn_s_sleep(1); \
;     if ((++_sp & 255u) == 0u) { if (xb_ld(&(bar)[XB_TMO])) break; if (_sp > XB_SPIN_CAP) { atomicAdd(&(bar)[XB_TMO], 1u); break; } } } } while (0)
; __device__ __forceinline__ void xcd_barrier(const XcdBarrier& b) {
;     ...
;         if (old + 1u == (gen + 1u) * nloc) {
;             __builtin_amdgcn_fence(__ATOMIC_RELEASE, "agent");
;             asm volatile("s_waitcnt vmcnt(0)" ::: "memory");
;             const unsigned og = xb_add(&bar[XB_TOP], 1u);
;             const unsigned tg = og / nx;
;             if (og + 1u == (tg + 1u) * nx) xb_add(&bar[XB_TOPGEN], 1u);
;             else XB_SPIN(xb_ld(&bar[XB_TOPGEN]) == tg, bar);
;             __builtin_amdgcn_fence(__ATOMIC_ACQUIRE, "agent");
;             xb_add(&bar[XB_XGEN(b.x)], 1u);
;             asm volatile("s_waitcnt vmcnt(0)" ::: "memory");
.LBB0_232:
	s_or_b64 exec, exec, s[8:9]
	v_cvt_f32_u32_e32 v3, v0
	s_waitcnt vmcnt(0)
	v_readfirstlane_b32 s6, v2
	s_mov_b64 s[10:11], 0
	v_rcp_iflag_f32_e32 v3, v3
	v_add_u32_e32 v1, s6, v1
	v_add_u32_e32 v4, 1, v1
	s_add_u32 s6, s2, 0x83500
	v_mul_f32_e32 v2, 0x4f7ffffe, v3
	v_cvt_u32_f32_e32 v2, v2
	v_sub_u32_e32 v3, 0, v0
	s_addc_u32 s7, s3, 0
	v_mul_lo_u32 v3, v3, v2
	v_mul_hi_u32 v3, v2, v3
	v_add_u32_e32 v2, v2, v3
	v_mul_hi_u32 v2, v1, v2
	v_mul_lo_u32 v3, v2, v0
	v_sub_u32_e32 v1, v1, v3
	v_add_u32_e32 v5, 1, v2
	v_cmp_ge_u32_e32 vcc, v1, v0
	v_sub_u32_e32 v3, v1, v0
	s_nop 0
	v_cndmask_b32_e32 v2, v2, v5, vcc
	v_cndmask_b32_e32 v1, v1, v3, vcc
	v_add_u32_e32 v3, 1, v2
	v_cmp_ge_u32_e32 vcc, v1, v0
	s_nop 1
	v_cndmask_b32_e32 v2, v2, v3, vcc
	v_mul_lo_u32 v1, v0, v2
	v_add_u32_e32 v0, v1, v0
	v_mov_b32_e32 v2, v0
	v_cmp_ne_u32_e32 vcc, v4, v0
	v_mov_b64_e32 v[0:1], s[6:7]
	s_and_saveexec_b64 s[8:9], vcc
	s_cbranch_execz .LBB0_244
	global_load_dword v0, v113, s[6:7] offset:-256 sc1
	s_mov_b64 s[14:15], 0
	s_waitcnt vmcnt(0)
	v_cmp_lt_u32_e32 vcc, v0, v2
	s_and_saveexec_b64 s[12:13], vcc
	s_cbranch_execz .LBB0_243
	s_add_u32 s10, s2, 0x80200
	s_addc_u32 s11, s3, 0
	s_mov_b32 s22, 1
	s_mov_b64 s[2:3], 0
	s_branch .LBB0_236

; __device__ __forceinline__ unsigned xb_ld(unsigned* p)              { return __hip_atomic_load(p, __ATOMIC_RELAXED, __HIP_MEMORY_SCOPE_AGENT); }
; #define XB_SPIN(cond, bar) do { unsigned _sp = 0; while (cond) { __builtin_amdgcn_s_sleep(1); \
;     if ((++_sp & 255u) == 0u) { if (xb_ld(&(bar)[XB_TMO])) break; if (_sp > XB_SPIN_CAP) { atomicAdd(&(bar)[XB_TMO], 1u); break; } } } } while (0)
; __device__ __forceinline__ void xcd_barrier(const XcdBarrier& b) {
;     ...
;             else XB_SPIN(xb_ld(&bar[XB_TOPGEN]) == tg, bar);
.LBB0_240:
	global_load_dword v0, v113, s[6:7] offset:-256 sc1
	s_add_i32 s22, s22, 1
	s_mov_b64 s[18:19], -1
	s_waitcnt vmcnt(0)
	v_cmp_ge_u32_e32 vcc, v0, v2
	s_orn2_b64 s[16:17], vcc, exec
	s_branch .LBB0_235

; __device__ __forceinline__ unsigned xb_add(unsigned* p, unsigned v) { return __hip_atomic_fetch_add(p, v, __ATOMIC_RELAXED, __HIP_MEMORY_SCOPE_AGENT); }
; __device__ __forceinline__ void xcd_barrier(const XcdBarrier& b) {
;     ...
;             __builtin_amdgcn_fence(__ATOMIC_ACQUIRE, "agent");
;             xb_add(&bar[XB_XGEN(b.x)], 1u);
;             asm volatile("s_waitcnt vmcnt(0)" ::: "memory");
.LBB0_246:
	s_or_b64 exec, exec, s[2:3]
	s_mov_b64 s[2:3], exec
	v_mbcnt_lo_u32_b32 v0, s2, 0
	v_mbcnt_hi_u32_b32 v0, s3, v0
	v_cmp_eq_u32_e32 vcc, 0, v0
	s_waitcnt vmcnt(0)
	buffer_inv sc1
	s_and_saveexec_b64 s[6:7], vcc
	s_cbranch_execz .LBB0_248
	s_bcnt1_i32_b64 s2, s[2:3]
	v_mov_b32_e32 v0, s2
.LBB0_248:
	s_or_b64 exec, exec, s[6:7]
	s_waitcnt vmcnt(0)

; __device__ __forceinline__ unsigned xb_ld(unsigned* p)              { return __hip_atomic_load(p, __ATOMIC_RELAXED, __HIP_MEMORY_SCOPE_AGENT); }
; __device__ __forceinline__ unsigned xb_add(unsigned* p, unsigned v) { return __hip_atomic_fetch_add(p, v, __ATOMIC_RELAXED, __HIP_MEMORY_SCOPE_AGENT); }
; #define XB_SPIN(cond, bar) do { unsigned _sp = 0; while (cond) { __builtin_amdgcn_s_sleep(1); \
;     if ((++_sp & 255u) == 0u) { if (xb_ld(&(bar)[XB_TMO])) break; if (_sp > XB_SPIN_CAP) { atomicAdd(&(bar)[XB_TMO], 1u); break; } } } } while (0)
; __device__ __forceinline__ void xcd_barrier(const XcdBarrier& b) {
;     ...
;         const unsigned old = xb_add(&bar[XB_XSUB(b.x)], 1u);
;         const unsigned gen = old / nloc;
;         if (old + 1u == (gen + 1u) * nloc) {
;             __builtin_amdgcn_fence(__ATOMIC_RELEASE, "agent");
;             asm volatile("s_waitcnt vmcnt(0)" ::: "memory");
;             const unsigned og = xb_add(&bar[XB_TOP], 1u);
;             const unsigned tg = og / nx;
;             if (og + 1u == (tg + 1u) * nx) xb_add(&bar[XB_TOPGEN], 1u);
;             else XB_SPIN(xb_ld(&bar[XB_TOPGEN]) == tg, bar);
;             __builtin_amdgcn_fence(__ATOMIC_ACQUIRE, "agent");
;             xb_add(&bar[XB_XGEN(b.x)], 1u);
;             asm volatile("s_waitcnt vmcnt(0)" ::: "memory");
;         } else {
;             XB_SPIN(xb_ld(&bar[XB_XGEN(b.x)]) == gen, bar);
.LBB0_351:
	s_or_b64 exec, exec, s[10:11]
	v_cvt_f32_u32_e32 v4, v2
	s_waitcnt vmcnt(0)
	v_readfirstlane_b32 s8, v3
	v_sub_u32_e32 v3, 0, v2
	v_rcp_iflag_f32_e32 v4, v4
	v_add_u32_e32 v5, s8, v1
	v_mul_f32_e32 v4, 0x4f7ffffe, v4
	v_cvt_u32_f32_e32 v4, v4
	v_mul_lo_u32 v1, v3, v4
	v_mul_hi_u32 v1, v4, v1
	v_add_u32_e32 v1, v4, v1
	v_mul_hi_u32 v1, v5, v1
	v_mul_lo_u32 v3, v1, v2
	v_sub_u32_e32 v3, v5, v3
	v_add_u32_e32 v4, 1, v1
	v_cmp_ge_u32_e32 vcc, v3, v2
	s_nop 1
	v_cndmask_b32_e32 v1, v1, v4, vcc
	v_sub_u32_e32 v4, v3, v2
	v_cndmask_b32_e32 v3, v3, v4, vcc
	v_add_u32_e32 v4, 1, v1
	v_cmp_ge_u32_e32 vcc, v3, v2
	v_add_u32_e32 v3, 1, v5
	s_nop 0
	v_cndmask_b32_e32 v1, v1, v4, vcc
	v_mul_lo_u32 v4, v2, v1
	v_add_u32_e32 v2, v4, v2
	v_cmp_ne_u32_e32 vcc, v3, v2
	s_and_saveexec_b64 s[8:9], vcc
	s_xor_b64 s[8:9], exec, s[8:9]
	s_cbranch_execz .LBB0_365
	s_waitcnt lgkmcnt(0)
	v_add_u32_e32 v1, 1, v1
	v_mul_lo_u32 v1, v1, v0
	s_add_u32 s14, s4, 0x81000
	s_addc_u32 s15, s5, 0
	global_load_dword v0, v237, s[14:15] offset:1024 sc1
	s_add_u32 s14, s4, 0x83400
	s_addc_u32 s15, s5, 0
	s_waitcnt vmcnt(0)
	v_cmp_lt_u32_e32 vcc, v0, v1
	s_and_saveexec_b64 s[10:11], vcc
	s_cbranch_execz .LBB0_364
	s_add_u32 s12, s4, 0x80200
	s_addc_u32 s13, s5, 0
	s_mov_b32 s26, 1
	s_mov_b64 s[16:17], 0
	s_branch .LBB0_355

; __device__ __forceinline__ unsigned xb_ld(unsigned* p)              { return __hip_atomic_load(p, __ATOMIC_RELAXED, __HIP_MEMORY_SCOPE_AGENT); }
; #define XB_SPIN(cond, bar) do { unsigned _sp = 0; while (cond) { __builtin_amdgcn_s_sleep(1); \
;     if ((++_sp & 255u) == 0u) { if (xb_ld(&(bar)[XB_TMO])) break; if (_sp > XB_SPIN_CAP) { atomicAdd(&(bar)[XB_TMO], 1u); break; } } } } while (0)
; __device__ __forceinline__ void xcd_barrier(const XcdBarrier& b) {
;     ...
;             XB_SPIN(xb_ld(&bar[XB_XGEN(b.x)]) == gen, bar);
.LBB0_359:
	global_load_dword v0, v113, s[14:15] sc1
	s_add_i32 s26, s26, 1
	s_mov_b64 s[22:23], -1
	s_waitcnt vmcnt(0)
	v_cmp_ge_u32_e32 vcc, v0, v1
	s_orn2_b64 s[20:21], vcc, exec
	s_branch .LBB0_354

; __device__ __forceinline__ unsigned xb_ld(unsigned* p)              { return __hip_atomic_load(p, __ATOMIC_RELAXED, __HIP_MEMORY_SCOPE_AGENT); }
; __device__ __forceinline__ unsigned xb_add(unsigned* p, unsigned v) { return __hip_atomic_fetch_add(p, v, __ATOMIC_RELAXED, __HIP_MEMORY_SCOPE_AGENT); }
; #define XB_SPIN(cond, bar) do { unsigned _sp = 0; while (cond) { __builtin_amdgcn_s_sleep(1); \
;     if ((++_sp & 255u) == 0u) { if (xb_ld(&(bar)[XB_TMO])) break; if (_sp > XB_SPIN_CAP) { atomicAdd(&(bar)[XB_TMO], 1u); break; } } } } while (0)
; __device__ __forceinline__ void xcd_barrier(const XcdBarrier& b) {
;     ...
;         if (old + 1u == (gen + 1u) * nloc) {
;             __builtin_amdgcn_fence(__ATOMIC_RELEASE, "agent");
;             asm volatile("s_waitcnt vmcnt(0)" ::: "memory");
;             const unsigned og = xb_add(&bar[XB_TOP], 1u);
;             const unsigned tg = og / nx;
;             if (og + 1u == (tg + 1u) * nx) xb_add(&bar[XB_TOPGEN], 1u);
;             else XB_SPIN(xb_ld(&bar[XB_TOPGEN]) == tg, bar);
;             __builtin_amdgcn_fence(__ATOMIC_ACQUIRE, "agent");
;             xb_add(&bar[XB_XGEN(b.x)], 1u);
;             asm volatile("s_waitcnt vmcnt(0)" ::: "memory");
.LBB0_368:
	s_or_b64 exec, exec, s[10:11]
	v_cvt_f32_u32_e32 v3, v0
	s_waitcnt vmcnt(0)
	v_readfirstlane_b32 s8, v2
	s_mov_b64 s[12:13], 0
	v_rcp_iflag_f32_e32 v3, v3
	v_add_u32_e32 v1, s8, v1
	v_add_u32_e32 v4, 1, v1
	s_add_u32 s8, s4, 0x83500
	v_mul_f32_e32 v2, 0x4f7ffffe, v3
	v_cvt_u32_f32_e32 v2, v2
	v_sub_u32_e32 v3, 0, v0
	s_addc_u32 s9, s5, 0
	v_mul_lo_u32 v3, v3, v2
	v_mul_hi_u32 v3, v2, v3
	v_add_u32_e32 v2, v2, v3
	v_mul_hi_u32 v2, v1, v2
	v_mul_lo_u32 v3, v2, v0
	v_sub_u32_e32 v1, v1, v3
	v_add_u32_e32 v5, 1, v2
	v_cmp_ge_u32_e32 vcc, v1, v0
	v_sub_u32_e32 v3, v1, v0
	s_nop 0
	v_cndmask_b32_e32 v2, v2, v5, vcc
	v_cndmask_b32_e32 v1, v1, v3, vcc
	v_add_u32_e32 v3, 1, v2
	v_cmp_ge_u32_e32 vcc, v1, v0
	s_nop 1
	v_cndmask_b32_e32 v2, v2, v3, vcc
	v_mul_lo_u32 v1, v0, v2
	v_add_u32_e32 v0, v1, v0
	v_mov_b32_e32 v2, v0
	v_cmp_ne_u32_e32 vcc, v4, v0
	v_mov_b64_e32 v[0:1], s[8:9]
	s_and_saveexec_b64 s[10:11], vcc
	s_cbranch_execz .LBB0_380
	global_load_dword v0, v113, s[8:9] offset:-256 sc1
	s_mov_b64 s[16:17], 0
	s_waitcnt vmcnt(0)
	v_cmp_lt_u32_e32 vcc, v0, v2
	s_and_saveexec_b64 s[14:15], vcc
	s_cbranch_execz .LBB0_379
	s_add_u32 s12, s4, 0x80200
	s_addc_u32 s13, s5, 0
	s_mov_b32 s24, 1
	s_mov_b64 s[4:5], 0
	s_branch .LBB0_372

; __device__ __forceinline__ unsigned xb_ld(unsigned* p)              { return __hip_atomic_load(p, __ATOMIC_RELAXED, __HIP_MEMORY_SCOPE_AGENT); }
; #define XB_SPIN(cond, bar) do { unsigned _sp = 0; while (cond) { __builtin_amdgcn_s_sleep(1); \
;     if ((++_sp & 255u) == 0u) { if (xb_ld(&(bar)[XB_TMO])) break; if (_sp > XB_SPIN_CAP) { atomicAdd(&(bar)[XB_TMO], 1u); break; } } } } while (0)
; __device__ __forceinline__ void xcd_barrier(const XcdBarrier& b) {
;     ...
;             else XB_SPIN(xb_ld(&bar[XB_TOPGEN]) == tg, bar);
.LBB0_376:
	global_load_dword v0, v113, s[8:9] offset:-256 sc1
	s_add_i32 s24, s24, 1
	s_mov_b64 s[20:21], -1
	s_waitcnt vmcnt(0)
	v_cmp_ge_u32_e32 vcc, v0, v2
	s_orn2_b64 s[18:19], vcc, exec
	s_branch .LBB0_371

; __device__ __forceinline__ unsigned xb_add(unsigned* p, unsigned v) { return __hip_atomic_fetch_add(p, v, __ATOMIC_RELAXED, __HIP_MEMORY_SCOPE_AGENT); }
; __device__ __forceinline__ void xcd_barrier(const XcdBarrier& b) {
;     ...
;             __builtin_amdgcn_fence(__ATOMIC_ACQUIRE, "agent");
;             xb_add(&bar[XB_XGEN(b.x)], 1u);
;             asm volatile("s_waitcnt vmcnt(0)" ::: "memory");
.LBB0_382:
	s_or_b64 exec, exec, s[4:5]
	s_mov_b64 s[4:5], exec
	v_mbcnt_lo_u32_b32 v0, s4, 0
	v_mbcnt_hi_u32_b32 v0, s5, v0
	v_cmp_eq_u32_e32 vcc, 0, v0
	s_waitcnt vmcnt(0)
	buffer_inv sc1
	s_and_saveexec_b64 s[8:9], vcc
	s_cbranch_execz .LBB0_384
	s_bcnt1_i32_b64 s4, s[4:5]
	v_mov_b32_e32 v0, s4
.LBB0_384:
	s_or_b64 exec, exec, s[8:9]
	s_waitcnt vmcnt(0)

; __device__ __forceinline__ unsigned xb_ld(unsigned* p)              { return __hip_atomic_load(p, __ATOMIC_RELAXED, __HIP_MEMORY_SCOPE_AGENT); }
; __device__ __forceinline__ unsigned xb_add(unsigned* p, unsigned v) { return __hip_atomic_fetch_add(p, v, __ATOMIC_RELAXED, __HIP_MEMORY_SCOPE_AGENT); }
; #define XB_SPIN(cond, bar) do { unsigned _sp = 0; while (cond) { __builtin_amdgcn_s_sleep(1); \
;     if ((++_sp & 255u) == 0u) { if (xb_ld(&(bar)[XB_TMO])) break; if (_sp > XB_SPIN_CAP) { atomicAdd(&(bar)[XB_TMO], 1u); break; } } } } while (0)
; __device__ __forceinline__ void xcd_barrier(const XcdBarrier& b) {
;     ...
;         const unsigned old = xb_add(&bar[XB_XSUB(b.x)], 1u);
;         const unsigned gen = old / nloc;
;         if (old + 1u == (gen + 1u) * nloc) {
;             __builtin_amdgcn_fence(__ATOMIC_RELEASE, "agent");
;             asm volatile("s_waitcnt vmcnt(0)" ::: "memory");
;             const unsigned og = xb_add(&bar[XB_TOP], 1u);
;             const unsigned tg = og / nx;
;             if (og + 1u == (tg + 1u) * nx) xb_add(&bar[XB_TOPGEN], 1u);
;             else XB_SPIN(xb_ld(&bar[XB_TOPGEN]) == tg, bar);
;             __builtin_amdgcn_fence(__ATOMIC_ACQUIRE, "agent");
;             xb_add(&bar[XB_XGEN(b.x)], 1u);
;             asm volatile("s_waitcnt vmcnt(0)" ::: "memory");
;         } else {
;             XB_SPIN(xb_ld(&bar[XB_XGEN(b.x)]) == gen, bar);
.LBB0_484:
	s_or_b64 exec, exec, s[8:9]
	v_cvt_f32_u32_e32 v4, v2
	s_waitcnt vmcnt(0)
	v_readfirstlane_b32 s6, v3
	v_sub_u32_e32 v3, 0, v2
	v_rcp_iflag_f32_e32 v4, v4
	v_add_u32_e32 v5, s6, v1
	v_mul_f32_e32 v4, 0x4f7ffffe, v4
	v_cvt_u32_f32_e32 v4, v4
	v_mul_lo_u32 v1, v3, v4
	v_mul_hi_u32 v1, v4, v1
	v_add_u32_e32 v1, v4, v1
	v_mul_hi_u32 v1, v5, v1
	v_mul_lo_u32 v3, v1, v2
	v_sub_u32_e32 v3, v5, v3
	v_add_u32_e32 v4, 1, v1
	v_cmp_ge_u32_e32 vcc, v3, v2
	s_nop 1
	v_cndmask_b32_e32 v1, v1, v4, vcc
	v_sub_u32_e32 v4, v3, v2
	v_cndmask_b32_e32 v3, v3, v4, vcc
	v_add_u32_e32 v4, 1, v1
	v_cmp_ge_u32_e32 vcc, v3, v2
	v_add_u32_e32 v3, 1, v5
	s_nop 0
	v_cndmask_b32_e32 v1, v1, v4, vcc
	v_mul_lo_u32 v4, v2, v1
	v_add_u32_e32 v2, v4, v2
	v_cmp_ne_u32_e32 vcc, v3, v2
	s_and_saveexec_b64 s[6:7], vcc
	s_xor_b64 s[6:7], exec, s[6:7]
	s_cbranch_execz .LBB0_498
	s_waitcnt lgkmcnt(0)
	v_add_u32_e32 v1, 1, v1
	v_mul_lo_u32 v1, v1, v0
	s_add_u32 s12, s2, 0x81000
	s_addc_u32 s13, s3, 0
	global_load_dword v0, v237, s[12:13] offset:1024 sc1
	s_add_u32 s12, s2, 0x83400
	s_addc_u32 s13, s3, 0
	s_waitcnt vmcnt(0)
	v_cmp_lt_u32_e32 vcc, v0, v1
	s_and_saveexec_b64 s[8:9], vcc
	s_cbranch_execz .LBB0_497
	s_add_u32 s10, s2, 0x80200
	s_addc_u32 s11, s3, 0
	s_mov_b32 s24, 1
	s_mov_b64 s[14:15], 0
	s_branch .LBB0_488

; __device__ __forceinline__ unsigned xb_add(unsigned* p, unsigned v) { return __hip_atomic_fetch_add(p, v, __ATOMIC_RELAXED, __HIP_MEMORY_SCOPE_AGENT); }
; __device__ __forceinline__ void xcd_barrier(const XcdBarrier& b) {
;     ...
;             __builtin_amdgcn_fence(__ATOMIC_ACQUIRE, "agent");
;             xb_add(&bar[XB_XGEN(b.x)], 1u);
;             asm volatile("s_waitcnt vmcnt(0)" ::: "memory");
.LBB0_515:
	s_or_b64 exec, exec, s[2:3]
	s_mov_b64 s[2:3], exec
	v_mbcnt_lo_u32_b32 v0, s2, 0
	v_mbcnt_hi_u32_b32 v0, s3, v0
	v_cmp_eq_u32_e32 vcc, 0, v0
	s_waitcnt vmcnt(0)
	buffer_inv sc1
	s_and_saveexec_b64 s[6:7], vcc
	s_cbranch_execz .LBB0_517
	s_bcnt1_i32_b64 s2, s[2:3]
	v_mov_b32_e32 v0, s2
.LBB0_517:
	s_or_b64 exec, exec, s[6:7]
	s_waitcnt vmcnt(0)

; __device__ __forceinline__ unsigned xb_add(unsigned* p, unsigned v) { return __hip_atomic_fetch_add(p, v, __ATOMIC_RELAXED, __HIP_MEMORY_SCOPE_AGENT); }
; __device__ __forceinline__ void xcd_barrier(const XcdBarrier& b) {
;     ...
;             __builtin_amdgcn_fence(__ATOMIC_ACQUIRE, "agent");
;             xb_add(&bar[XB_XGEN(b.x)], 1u);
;             asm volatile("s_waitcnt vmcnt(0)" ::: "memory");
.LBB0_992:
	s_or_b64 exec, exec, s[2:3]
	s_mov_b64 s[2:3], exec
	v_mbcnt_lo_u32_b32 v0, s2, 0
	v_mbcnt_hi_u32_b32 v0, s3, v0
	v_cmp_eq_u32_e32 vcc, 0, v0
	s_waitcnt vmcnt(0)
	buffer_inv sc1
	s_and_saveexec_b64 s[6:7], vcc
	s_cbranch_execz .LBB0_994
	s_bcnt1_i32_b64 s2, s[2:3]
	v_mov_b32_e32 v0, s2
.LBB0_994:
	s_or_b64 exec, exec, s[6:7]
	s_waitcnt vmcnt(0)

; __device__ __forceinline__ unsigned xb_add(unsigned* p, unsigned v) { return __hip_atomic_fetch_add(p, v, __ATOMIC_RELAXED, __HIP_MEMORY_SCOPE_AGENT); }
; __device__ __forceinline__ void xcd_barrier(const XcdBarrier& b) {
;     ...
;             __builtin_amdgcn_fence(__ATOMIC_ACQUIRE, "agent");
;             xb_add(&bar[XB_XGEN(b.x)], 1u);
;             asm volatile("s_waitcnt vmcnt(0)" ::: "memory");
.LBB0_1070:
	s_or_b64 exec, exec, s[2:3]
	s_mov_b64 s[2:3], exec
	v_mbcnt_lo_u32_b32 v0, s2, 0
	v_mbcnt_hi_u32_b32 v0, s3, v0
	v_cmp_eq_u32_e32 vcc, 0, v0
	s_waitcnt vmcnt(0)
	buffer_inv sc1
	s_and_saveexec_b64 s[6:7], vcc
	s_cbranch_execz .LBB0_1072
	s_bcnt1_i32_b64 s2, s[2:3]
	v_mov_b32_e32 v0, s2
.LBB0_1072:
	s_or_b64 exec, exec, s[6:7]
	s_waitcnt vmcnt(0)

; __device__ __forceinline__ unsigned xb_add(unsigned* p, unsigned v) { return __hip_atomic_fetch_add(p, v, __ATOMIC_RELAXED, __HIP_MEMORY_SCOPE_AGENT); }
; __device__ __forceinline__ void xcd_barrier(const XcdBarrier& b) {
;     ...
;             __builtin_amdgcn_fence(__ATOMIC_ACQUIRE, "agent");
;             xb_add(&bar[XB_XGEN(b.x)], 1u);
;             asm volatile("s_waitcnt vmcnt(0)" ::: "memory");
.LBB0_1351:
	s_or_b64 exec, exec, s[2:3]
	s_mov_b64 s[2:3], exec
	v_mbcnt_lo_u32_b32 v0, s2, 0
	v_mbcnt_hi_u32_b32 v0, s3, v0
	v_cmp_eq_u32_e32 vcc, 0, v0
	s_waitcnt vmcnt(0)
	buffer_inv sc1
	s_and_saveexec_b64 s[6:7], vcc
	s_cbranch_execz .LBB0_1353
	s_bcnt1_i32_b64 s2, s[2:3]
	v_mov_b32_e32 v0, s2
.LBB0_1353:
	s_or_b64 exec, exec, s[6:7]
	s_waitcnt vmcnt(0)

; __device__ __forceinline__ unsigned xb_add(unsigned* p, unsigned v) { return __hip_atomic_fetch_add(p, v, __ATOMIC_RELAXED, __HIP_MEMORY_SCOPE_AGENT); }
; __device__ __forceinline__ void xcd_barrier(const XcdBarrier& b) {
;     ...
;             __builtin_amdgcn_fence(__ATOMIC_ACQUIRE, "agent");
;             xb_add(&bar[XB_XGEN(b.x)], 1u);
;             asm volatile("s_waitcnt vmcnt(0)" ::: "memory");
.LBB0_1413:
	s_or_b64 exec, exec, s[2:3]
	s_mov_b64 s[2:3], exec
	v_mbcnt_lo_u32_b32 v0, s2, 0
	v_mbcnt_hi_u32_b32 v0, s3, v0
	v_cmp_eq_u32_e32 vcc, 0, v0
	s_waitcnt vmcnt(0)
	buffer_inv sc1
	s_and_saveexec_b64 s[6:7], vcc
	s_cbranch_execz .LBB0_1415
	s_bcnt1_i32_b64 s2, s[2:3]
	v_mov_b32_e32 v0, s2
.LBB0_1415:
	s_or_b64 exec, exec, s[6:7]
	s_waitcnt vmcnt(0)

; __device__ __forceinline__ unsigned xb_add(unsigned* p, unsigned v) { return __hip_atomic_fetch_add(p, v, __ATOMIC_RELAXED, __HIP_MEMORY_SCOPE_AGENT); }
; __device__ __forceinline__ void xcd_barrier(const XcdBarrier& b) {
;     ...
;             __builtin_amdgcn_fence(__ATOMIC_ACQUIRE, "agent");
;             xb_add(&bar[XB_XGEN(b.x)], 1u);
;             asm volatile("s_waitcnt vmcnt(0)" ::: "memory");
.LBB0_1613:
	s_or_b64 exec, exec, s[2:3]
	s_mov_b64 s[2:3], exec
	v_mbcnt_lo_u32_b32 v0, s2, 0
	v_mbcnt_hi_u32_b32 v0, s3, v0
	v_cmp_eq_u32_e32 vcc, 0, v0
	s_waitcnt vmcnt(0)
	buffer_inv sc1
	s_and_saveexec_b64 s[6:7], vcc
	s_cbranch_execz .LBB0_1615
	s_bcnt1_i32_b64 s2, s[2:3]
	v_mov_b32_e32 v0, s2
.LBB0_1615:
	s_or_b64 exec, exec, s[6:7]
	s_waitcnt vmcnt(0)

; __device__ __forceinline__ unsigned xb_add(unsigned* p, unsigned v) { return __hip_atomic_fetch_add(p, v, __ATOMIC_RELAXED, __HIP_MEMORY_SCOPE_AGENT); }
; __device__ __forceinline__ void xcd_barrier(const XcdBarrier& b) {
;     ...
;             __builtin_amdgcn_fence(__ATOMIC_ACQUIRE, "agent");
;             xb_add(&bar[XB_XGEN(b.x)], 1u);
;             asm volatile("s_waitcnt vmcnt(0)" ::: "memory");
.LBB0_1706:
	s_or_b64 exec, exec, s[2:3]
	s_mov_b64 s[2:3], exec
	v_mbcnt_lo_u32_b32 v0, s2, 0
	v_mbcnt_hi_u32_b32 v0, s3, v0
	v_cmp_eq_u32_e32 vcc, 0, v0
	s_waitcnt vmcnt(0)
	buffer_inv sc1
	s_and_saveexec_b64 s[6:7], vcc
	s_cbranch_execz .LBB0_1708
	s_bcnt1_i32_b64 s2, s[2:3]
	v_mov_b32_e32 v0, s2
.LBB0_1708:
	s_or_b64 exec, exec, s[6:7]
	s_waitcnt vmcnt(0)
